# SGPR-base DMA addressing also in the 64-row residual piece loops
# baseline (speedup 1.0000x reference)
; DI int tid_() { int t = threadIdx.x; asm volatile("" : "+v"(t)); return t; }
;     ...
;   const int tid = tid_(), w = tid >> 6, l = tid & 63, r16 = l & 15, q4 = l >> 4;
;   const int wm = w >> 2, wn = w & 3;
;   f32x4 acc[MT][4];
; #pragma unroll
;   for (int a = 0; a < MT; ++a)
; #pragma unroll
;     for (int b = 0; b < 4; ++b) { acc[a][b][0] = 0.f; acc[a][b][1] = 0.f; acc[a][b][2] = 0.f; acc[a][b][3] = 0.f; }
;   const int srow = tid >> 3, slog = (tid & 7) ^ ((tid >> 4) & 7);
;   const bf16_t* Ag = A + (size_t)(m0 + srow) * lda + slog * 8;
;   const bf16_t* Bg0 = B + (size_t)min(n0 + srow, N - 1) * ldb + slog * 8;
;   const bf16_t* Bg1 = B + (size_t)min(n0 + srow + 64, N - 1) * ldb + slog * 8;
;   const bf16_t* Bg2 = B + (size_t)min(n0 + srow + 128, N - 1) * ldb + slog * 8;
;   const bf16_t* Bg3 = B + (size_t)min(n0 + srow + 192, N - 1) * ldb + slog * 8;
;   char* wbase = smem + w * 1024;
;     ...
;   const int nk = K >> 6;
;   __syncthreads();
;   STAGE_TILE(0, 0)
;   asm volatile("s_waitcnt vmcnt(0)" ::: "memory");
;   __syncthreads();
; template <int TMI, class F>
; DI void for_tiles_xcd(int MT, int NT, const F& f) {
;     ...
;   for (int q = b; q < npieces; q += G) {
;     int mt, nt; decode(total_full + q / PIECES, mt, nt);
;     f(mt * 256 + (q % PIECES) * 64 * TMI, nt, std::integral_constant<int, TMI>{});
.LBB0_58:
	s_lshl_b32 s14, s23, 2
	s_sub_i32 s14, s21, s14
	s_lshl_b32 s27, s31, 8
	s_lshl_b32 s14, s14, 6
	v_mov_b32_e32 v14, v0
	s_add_i32 s27, s27, s14
	s_lshl_b32 s23, s30, 8
	v_readlane_b32 s52, v253, 40
	v_lshrrev_b32_e32 v15, 4, v14
	v_ashrrev_i32_e32 v4, 3, v14
	v_xor_b32_e32 v6, v15, v14
	v_add_u32_e32 v16, s27, v4
	v_add_u32_e32 v4, s23, v4
	v_readlane_b32 s54, v253, 42
	v_readlane_b32 s55, v253, 43
	v_lshlrev_b32_e32 v6, 4, v6
	v_min_i32_e32 v10, 0x3bf, v4
	v_min_i32_e32 v12, 0x37f, v4
	v_min_i32_e32 v18, 0x33f, v4
	v_ashrrev_i32_e32 v5, 6, v14
	v_mov_b64_e32 v[2:3], s[54:55]
	s_movk_i32 s30, 0x1600
	v_and_b32_e32 v190, 0x70, v6
	v_min_i32_e32 v17, 0x3ff, v4
	v_mov_b64_e32 v[6:7], s[2:3]
	v_add_u32_e32 v10, 64, v10
	v_add_u32_e32 v12, 0x80, v12
	v_add_u32_e32 v18, 0xc0, v18
	v_mad_i64_i32 v[2:3], s[14:15], v16, s30, v[2:3]
	v_mad_i64_i32 v[8:9], s[14:15], v17, s30, v[6:7]
	v_mad_i64_i32 v[10:11], s[14:15], v10, s30, v[6:7]
	v_mad_i64_i32 v[12:13], s[14:15], v12, s30, v[6:7]
	v_mad_i64_i32 v[6:7], s[14:15], v18, s30, v[6:7]
	v_lshl_add_u32 v48, v5, 10, 0
	v_lshl_add_u64 v[2:3], v[2:3], 0, v[190:191]
	v_readfirstlane_b32 s14, v48
	s_mov_b32 m0, s14
	s_barrier
	global_load_lds_dwordx4 v[2:3], off
	v_add_u32_e32 v2, 0x8000, v48
	v_lshl_add_u64 v[8:9], v[8:9], 0, v[190:191]
	v_readfirstlane_b32 s14, v2
	v_add_u32_e32 v2, 0xa000, v48
	s_mov_b32 m0, s14
	v_readfirstlane_b32 s14, v2
	v_add_u32_e32 v2, 0xc000, v48
	v_lshl_add_u64 v[10:11], v[10:11], 0, v[190:191]
	global_load_lds_dwordx4 v[8:9], off
	s_mov_b32 m0, s14
	v_readfirstlane_b32 s14, v2
	v_add_u32_e32 v2, 0xe000, v48
	v_lshl_add_u64 v[12:13], v[12:13], 0, v[190:191]
	global_load_lds_dwordx4 v[10:11], off
	s_mov_b32 m0, s14
	v_readfirstlane_b32 s14, v2
	v_lshl_add_u64 v[6:7], v[6:7], 0, v[190:191]
	global_load_lds_dwordx4 v[12:13], off
	s_mov_b32 m0, s14
	v_and_b32_e32 v46, 15, v14
	global_load_lds_dwordx4 v[6:7], off
	v_ashrrev_i32_e32 v44, 8, v14
	v_bfe_u32 v45, v14, 4, 2
	v_and_b32_e32 v47, 3, v5
	v_bfe_u32 v5, v14, 1, 3
	v_lshlrev_b32_e32 v8, 7, v46
	v_mad_i64_i32 v[2:3], s[14:15], v16, s30, 0
	v_mad_i64_i32 v[6:7], s[14:15], v17, s30, 0
	v_lshl_or_b32 v52, v44, 12, v8
	v_lshl_or_b32 v51, v47, 13, v8
	v_bitop3_b32 v8, v15, v5, 3 bitop3:0x6c
	v_bitop3_b32 v5, v45, v5, 4 bitop3:0x36
	v_lshlrev_b32_e32 v49, 4, v5
	v_ashrrev_i32_e32 v5, 31, v4
	s_mov_b64 s[14:15], 0x33f
	v_cmp_gt_i64_e32 vcc, s[14:15], v[4:5]
	v_lshlrev_b32_e32 v50, 4, v8
	v_bitop3_b32 v10, v15, 7, v14 bitop3:0x48
	v_cndmask_b32_e32 v8, v227, v4, vcc
	v_mad_i64_i32 v[8:9], s[14:15], v8, s30, 0
	v_lshlrev_b32_e32 v10, 4, v10
	s_mov_b64 s[14:15], 0x37f
	v_or_b32_e32 v8, v8, v10
	v_cmp_gt_i64_e32 vcc, s[14:15], v[4:5]
	v_lshl_add_u64 v[34:35], s[4:5], 0, v[8:9]
	s_waitcnt vmcnt(0)
	v_or_b32_e32 v2, v2, v10
	v_cndmask_b32_e32 v8, v197, v4, vcc
	v_mad_i64_i32 v[8:9], s[14:15], v8, s30, 0
	s_mov_b64 s[14:15], 0x3bf
	s_nop 0
	v_cmp_gt_i64_e32 vcc, s[14:15], v[4:5]
	v_or_b32_e32 v8, v8, v10
	v_or_b32_e32 v6, v6, v10
	v_cndmask_b32_e32 v4, v195, v4, vcc
	v_mad_i64_i32 v[4:5], s[14:15], v4, s30, 0
	v_readlane_b32 s14, v252, 44
	v_readlane_b32 s15, v252, 45
	v_or_b32_e32 v4, v4, v10
	v_lshl_add_u64 v[36:37], s[8:9], 0, v[8:9]
	v_lshl_add_u64 v[42:43], s[14:15], 0, v[2:3]
	v_mov_b32_e32 v2, 0
	v_lshl_add_u64 v[38:39], s[10:11], 0, v[4:5]
	v_lshl_add_u64 v[40:41], s[12:13], 0, v[6:7]
	s_mov_b64 s[14:15], 0
	s_mov_b32 s30, 0
	v_mov_b32_e32 v3, v2
	v_mov_b32_e32 v4, v2
	v_mov_b32_e32 v5, v2
	v_mov_b32_e32 v6, v2
	v_mov_b32_e32 v7, v2
	v_mov_b32_e32 v8, v2
	v_mov_b32_e32 v9, v2
	v_mov_b32_e32 v10, v2
	v_mov_b32_e32 v11, v2
	v_mov_b32_e32 v12, v2
	v_mov_b32_e32 v13, v2
	v_mov_b32_e32 v14, v2
	v_mov_b32_e32 v15, v2
	v_mov_b32_e32 v16, v2
	v_mov_b32_e32 v17, v2
	v_mov_b32_e32 v18, v2
	v_mov_b32_e32 v19, v2
	v_mov_b32_e32 v20, v2
	v_mov_b32_e32 v21, v2
	v_mov_b32_e32 v22, v2
	v_mov_b32_e32 v23, v2
	v_mov_b32_e32 v24, v2
	v_mov_b32_e32 v25, v2
	v_mov_b32_e32 v26, v2
	v_mov_b32_e32 v27, v2
	v_mov_b32_e32 v28, v2
	v_mov_b32_e32 v29, v2
	v_mov_b32_e32 v30, v2
	v_mov_b32_e32 v31, v2
	v_mov_b32_e32 v32, v2
	v_mov_b32_e32 v33, v2
	v_readlane_b32 s53, v253, 41
	v_readlane_b32 s56, v253, 44
	v_readlane_b32 s57, v253, 45
	v_readlane_b32 s58, v253, 46
	v_readlane_b32 s59, v253, 47
	v_readlane_b32 s60, v253, 48
	v_readlane_b32 s61, v253, 49
	v_readlane_b32 s62, v253, 50
	v_readlane_b32 s63, v253, 51
	v_readlane_b32 s64, v253, 52
	v_readlane_b32 s65, v253, 53
	v_readlane_b32 s66, v253, 54
	v_readlane_b32 s67, v253, 55
	s_waitcnt vmcnt(0) lgkmcnt(0)
	s_barrier
	v_readfirstlane_b32 s100, v40
	v_readfirstlane_b32 s101, v41
	s_nop 0
	s_sub_u32 s100, s100, 0x80
	s_subb_u32 s101, s101, 0
	v_subrev_u32_e32 v176, s100, v42
	v_subrev_u32_e32 v177, s100, v40
	v_subrev_u32_e32 v178, s100, v38
	v_subrev_u32_e32 v179, s100, v36
	v_subrev_u32_e32 v180, s100, v34
; #define MFMA16(a, b, c) __builtin_amdgcn_mfma_f32_16x16x32_bf16((a), (b), (c), 0, 0, 0)
;     ...
;   for (int kt = 0; kt < nk; ++kt) {
;     const int buf = kt & 1;
;     const char* cA = smem + buf * STAGE + (wm * 32 * MI + r16) * 128;
;     const char* cB = smem + buf * STAGE + 32768 + (wn * 64 + r16) * 128;
; #pragma unroll
;     for (int k2 = 0; k2 < 2; ++k2) {
;       if (k2 == 1 && kt + 1 < nk) STAGE_TILE(buf ^ 1, (kt + 1) * 64)
;       const int po = ((4 * k2 + q4) ^ swz) * 16;
;       bf16x8 bf[4];
; #pragma unroll
;       for (int nt = 0; nt < 4; ++nt) bf[nt] = *(const bf16x8*)(cB + nt * 16 * 128 + po);
;       bf16x8 afc = *(const bf16x8*)(cA + po);
; #pragma unroll
;       for (int a = 0; a < MT; ++a) {
;         bf16x8 afn = afc;
;         if (a + 1 < MT) afn = *(const bf16x8*)(cA + (a + 1) * 16 * 128 + po);
;         __builtin_amdgcn_sched_barrier(0);
; #pragma unroll
;         for (int nt = 0; nt < 4; ++nt) acc[a][nt] = MFMA16(bf[nt], afc, acc[a][nt]);
;         __builtin_amdgcn_sched_barrier(0);
;         afc = afn;
;       }
;     }
;     asm volatile("s_waitcnt vmcnt(0)" ::: "memory");
;     __syncthreads();
;   }
.LBB0_59:
	s_and_b32 s31, s30, 0x10000
	s_add_i32 s34, s31, 0
	v_add_u32_e32 v78, s34, v51
	v_add_u32_e32 v66, v78, v50
	v_add_u32_e32 v53, s34, v52
	ds_read_b128 v[54:57], v66 offset:32768
	ds_read_b128 v[58:61], v66 offset:34816
	ds_read_b128 v[62:65], v66 offset:36864
	ds_read_b128 v[66:69], v66 offset:38912
	v_add_u32_e32 v74, v53, v50
	ds_read_b128 v[70:73], v74
	ds_read_b128 v[74:77], v74 offset:2048
	s_waitcnt lgkmcnt(1)
	v_mfma_f32_16x16x32_bf16 v[30:33], v[54:57], v[70:73], v[30:33]
	v_mfma_f32_16x16x32_bf16 v[26:29], v[58:61], v[70:73], v[26:29]
	v_mfma_f32_16x16x32_bf16 v[22:25], v[62:65], v[70:73], v[22:25]
	v_mfma_f32_16x16x32_bf16 v[18:21], v[66:69], v[70:73], v[18:21]
	s_waitcnt lgkmcnt(0)
	v_mfma_f32_16x16x32_bf16 v[14:17], v[54:57], v[74:77], v[14:17]
	v_mfma_f32_16x16x32_bf16 v[10:13], v[58:61], v[74:77], v[10:13]
	v_mfma_f32_16x16x32_bf16 v[6:9], v[62:65], v[74:77], v[6:9]
	v_mfma_f32_16x16x32_bf16 v[2:5], v[66:69], v[74:77], v[2:5]
	s_xor_b32 s31, s31, 0x10000
	v_readfirstlane_b32 s34, v48
	s_nop 0
	s_add_u32 s34, s34, s31
	s_add_u32 m0, s34, 0x0
	s_nop 0
	global_load_lds_dwordx4 v176, s[100:101]
	s_add_u32 m0, s34, 0x8000
	s_nop 0
	global_load_lds_dwordx4 v177, s[100:101]
	s_add_u32 m0, s34, 0xa000
	s_nop 0
	global_load_lds_dwordx4 v178, s[100:101]
	s_add_u32 m0, s34, 0xc000
	s_nop 0
	global_load_lds_dwordx4 v179, s[100:101]
	s_add_u32 m0, s34, 0xe000
	s_nop 0
	global_load_lds_dwordx4 v180, s[100:101]
	v_add_u32_e32 v66, v78, v49
	ds_read_b128 v[54:57], v66 offset:32768
	ds_read_b128 v[58:61], v66 offset:34816
	ds_read_b128 v[62:65], v66 offset:36864
	ds_read_b128 v[66:69], v66 offset:38912
	v_add_u32_e32 v53, v53, v49
	ds_read_b128 v[70:73], v53
	ds_read_b128 v[74:77], v53 offset:2048
	s_waitcnt lgkmcnt(0)
	v_mfma_f32_16x16x32_bf16 v[30:33], v[54:57], v[70:73], v[30:33]
	v_mfma_f32_16x16x32_bf16 v[26:29], v[58:61], v[70:73], v[26:29]
	v_mfma_f32_16x16x32_bf16 v[22:25], v[62:65], v[70:73], v[22:25]
	v_mfma_f32_16x16x32_bf16 v[18:21], v[66:69], v[70:73], v[18:21]
	v_mfma_f32_16x16x32_bf16 v[14:17], v[54:57], v[74:77], v[14:17]
	v_mfma_f32_16x16x32_bf16 v[10:13], v[58:61], v[74:77], v[10:13]
	v_mfma_f32_16x16x32_bf16 v[6:9], v[62:65], v[74:77], v[6:9]
	v_mfma_f32_16x16x32_bf16 v[2:5], v[66:69], v[74:77], v[2:5]
	s_waitcnt vmcnt(0)
	s_add_u32 s100, s100, 0x80
	s_addc_u32 s101, s101, 0
	s_add_u32 s14, s14, 0x80
	s_addc_u32 s15, s15, 0
	s_add_i32 s30, s30, 0x10000
	s_cmpk_eq_i32 s14, 0x1580
	s_waitcnt vmcnt(0)
	s_barrier
	s_cbranch_scc0 .LBB0_59
	s_add_i32 s14, 0, 0x10000
	v_add_u32_e32 v42, s14, v52
	v_readlane_b32 s14, v254, 18
	s_nop 1
	v_add_u32_e32 v43, s14, v51
	v_add_u32_e32 v48, v43, v50
	ds_read_b128 v[34:37], v48
	ds_read_b128 v[38:41], v48 offset:2048
	ds_read_b128 v[52:55], v48 offset:4096
	ds_read_b128 v[56:59], v48 offset:6144
	v_add_u32_e32 v48, v42, v50
	ds_read_b128 v[60:63], v48
	ds_read_b128 v[64:67], v48 offset:2048
	s_waitcnt lgkmcnt(1)
	v_mfma_f32_16x16x32_bf16 v[30:33], v[34:37], v[60:63], v[30:33]
	v_mfma_f32_16x16x32_bf16 v[26:29], v[38:41], v[60:63], v[26:29]
	v_mfma_f32_16x16x32_bf16 v[22:25], v[52:55], v[60:63], v[22:25]
	v_mfma_f32_16x16x32_bf16 v[18:21], v[56:59], v[60:63], v[18:21]
	s_waitcnt lgkmcnt(0)
	v_mfma_f32_16x16x32_bf16 v[14:17], v[34:37], v[64:67], v[14:17]
	v_mfma_f32_16x16x32_bf16 v[10:13], v[38:41], v[64:67], v[10:13]
	v_mfma_f32_16x16x32_bf16 v[6:9], v[52:55], v[64:67], v[6:9]
	v_mfma_f32_16x16x32_bf16 v[2:5], v[56:59], v[64:67], v[2:5]
	v_add_u32_e32 v43, v43, v49
	ds_read_b128 v[34:37], v43
	ds_read_b128 v[38:41], v43 offset:2048
	ds_read_b128 v[50:53], v43 offset:4096
	ds_read_b128 v[54:57], v43 offset:6144
	v_add_u32_e32 v42, v42, v49
	ds_read_b128 v[58:61], v42
	ds_read_b128 v[62:65], v42 offset:2048
	s_waitcnt lgkmcnt(1)
	v_mfma_f32_16x16x32_bf16 v[30:33], v[34:37], v[58:61], v[30:33]
	v_mfma_f32_16x16x32_bf16 v[26:29], v[38:41], v[58:61], v[26:29]
	v_mfma_f32_16x16x32_bf16 v[22:25], v[50:53], v[58:61], v[22:25]
	v_mfma_f32_16x16x32_bf16 v[18:21], v[54:57], v[58:61], v[18:21]
	s_waitcnt lgkmcnt(0)
	v_mfma_f32_16x16x32_bf16 v[14:17], v[34:37], v[62:65], v[14:17]
	v_mfma_f32_16x16x32_bf16 v[10:13], v[38:41], v[62:65], v[10:13]
	v_mfma_f32_16x16x32_bf16 v[6:9], v[50:53], v[62:65], v[6:9]
	v_mfma_f32_16x16x32_bf16 v[2:5], v[54:57], v[62:65], v[2:5]
	v_or_b32_e32 v35, s27, v46
	v_lshlrev_b32_e32 v34, 6, v47
	v_lshl_add_u32 v54, v44, 5, v35
	v_lshlrev_b32_e32 v35, 2, v45
	v_or3_b32 v38, v34, v35, s23
	v_mul_hi_i32 v34, v54, s1
	v_lshrrev_b32_e32 v35, 31, v34
	v_ashrrev_i32_e32 v34, 11, v34
	v_add_u32_e32 v34, v34, v35
	v_mad_i32_i24 v35, v34, s90, v54
	s_movk_i32 s23, 0x100
	v_cmp_gt_i32_e32 vcc, s23, v35
	v_add_u32_e32 v36, 0xffffff00, v35
	v_ashrrev_i32_e32 v37, 31, v35
	v_readlane_b32 s36, v254, 1
	v_cndmask_b32_e64 v39, v34, 4, vcc
	v_cndmask_b32_e32 v37, 0, v37, vcc
	v_cndmask_b32_e32 v36, v36, v35, vcc
	v_ashrrev_i32_e32 v35, 31, v34
	v_cndmask_b32_e64 v40, 25, 20, vcc
	v_readlane_b32 s37, v254, 2
	v_lshlrev_b64 v[44:45], v40, v[34:35]
	v_lshlrev_b64 v[46:47], 12, v[36:37]
	v_add_u32_e32 v34, s17, v39
	v_mov_b64_e32 v[36:37], s[36:37]
	s_movk_i32 s27, 0x6000
	v_mad_i64_i32 v[34:35], s[14:15], v34, s27, v[36:37]
	v_readlane_b32 s14, v252, 26
	s_waitcnt vmcnt(0)
	s_barrier
; DI void phase_resid(char* smem, const Params& p, int layer, const bf16_t* A, int K, const bf16_t* W, int gate_idx, bool first) {
;     ...
;   auto ep = [&](int row, int col, float v0, float v1, float v2, float v3) {
;     const int b = row / TT, t = row - b * TT;
;     const float4 g = *(const float4*)(p.mod + (size_t)(layer * 5 + (t < CTXL ? 4 : b)) * 6144 + gate_idx * 1024 + col);
;     const float4 xo = *(const float4*)(xsrc_row(p, first, row) + col);
;     *(float4*)(xdst_row(p, row) + col) = make_float4(xo.x + g.x * v0, xo.y + g.y * v1, xo.z + g.z * v2, xo.w + g.w * v3);
;   };
	s_nop 0
	v_mov_b32_e32 v55, s14
	v_readlane_b32 s14, v252, 28
	v_readlane_b32 s68, v252, 5
	s_nop 0
	v_mov_b32_e32 v56, s14
	v_readlane_b32 s14, v252, 25
	v_cndmask_b32_e32 v43, v55, v56, vcc
	v_readlane_b32 s80, v252, 17
	v_mov_b32_e32 v57, s14
	v_readlane_b32 s14, v252, 27
	v_readlane_b32 s81, v252, 18
	v_readlane_b32 s82, v252, 19
	v_mov_b32_e32 v58, s14
	v_cndmask_b32_e32 v42, v57, v58, vcc
	global_load_dwordx2 v[42:43], v[42:43], off
	v_readlane_b32 s83, v252, 20
	s_mov_b64 s[30:31], 0x5000
	v_ashrrev_i32_e32 v39, 31, v38
	v_mov_b32_e32 v59, s81
	v_mov_b32_e32 v60, s83
	v_mov_b32_e32 v61, s80
	v_mov_b32_e32 v62, s82
	v_lshl_add_u64 v[40:41], v[34:35], 0, s[30:31]
	v_lshlrev_b64 v[34:35], 2, v[38:39]
	v_cndmask_b32_e32 v51, v59, v60, vcc
	v_cndmask_b32_e32 v50, v61, v62, vcc
	v_lshl_add_u64 v[48:49], v[40:41], 0, v[34:35]
	v_readlane_b32 s38, v254, 3
	v_readlane_b32 s39, v254, 4
	v_readlane_b32 s40, v254, 5
	v_readlane_b32 s41, v254, 6
	v_readlane_b32 s42, v254, 7
	v_readlane_b32 s43, v254, 8
	v_readlane_b32 s44, v254, 9
	v_readlane_b32 s45, v254, 10
	v_readlane_b32 s46, v254, 11
	v_readlane_b32 s47, v254, 12
	v_readlane_b32 s48, v254, 13
	v_readlane_b32 s49, v254, 14
	v_readlane_b32 s50, v254, 15
	v_readlane_b32 s51, v254, 16
	s_add_i32 s21, s21, s20
	s_cmp_ge_i32 s21, s16
	v_readlane_b32 s36, v255, 12
	v_readlane_b32 s69, v252, 6
	v_readlane_b32 s70, v252, 7
	v_readlane_b32 s71, v252, 8
	v_readlane_b32 s72, v252, 9
	v_readlane_b32 s73, v252, 10
	v_readlane_b32 s74, v252, 11
	v_readlane_b32 s75, v252, 12
	v_readlane_b32 s76, v252, 13
	v_readlane_b32 s77, v252, 14
	v_readlane_b32 s78, v252, 15
	v_readlane_b32 s79, v252, 16
	v_readlane_b32 s37, v255, 13
	v_readlane_b32 s38, v255, 14
	v_readlane_b32 s39, v255, 15
	v_readlane_b32 s40, v255, 16
	v_readlane_b32 s41, v255, 17
	v_readlane_b32 s42, v255, 18
	v_readlane_b32 s43, v255, 19
	v_readlane_b32 s44, v255, 20
	v_readlane_b32 s45, v255, 21
	v_readlane_b32 s46, v255, 22
	v_readlane_b32 s47, v255, 23
	v_readlane_b32 s48, v255, 24
	v_readlane_b32 s49, v255, 25
	v_readlane_b32 s50, v255, 26
	v_readlane_b32 s51, v255, 27
	s_waitcnt vmcnt(0)
	v_lshl_add_u64 v[42:43], v[42:43], 0, v[44:45]
	v_lshl_add_u64 v[42:43], v[42:43], 0, v[46:47]
	v_lshl_add_u64 v[44:45], v[50:51], 0, v[44:45]
	v_lshl_add_u64 v[42:43], v[42:43], 0, v[34:35]
	v_lshl_add_u64 v[44:45], v[44:45], 0, v[46:47]
	v_lshl_add_u64 v[44:45], v[44:45], 0, v[34:35]
	global_load_dwordx4 v[156:159], v[48:49], off
	global_load_dwordx4 v[160:163], v[48:49], off offset:64
	global_load_dwordx4 v[164:167], v[48:49], off offset:128
	global_load_dwordx4 v[168:171], v[48:49], off offset:192
	global_load_dwordx4 v[172:175], v[42:43], off
	global_load_dwordx4 v[176:179], v[42:43], off offset:64
	global_load_dwordx4 v[180:183], v[42:43], off offset:128
	global_load_dwordx4 v[184:187], v[42:43], off offset:192
	v_add_co_u32_e32 v42, vcc, 0x10000, v42
	s_nop 1
	v_addc_co_u32_e32 v43, vcc, 0, v43, vcc
	global_load_dwordx4 v[198:201], v[42:43], off
	global_load_dwordx4 v[202:205], v[42:43], off offset:64
	global_load_dwordx4 v[206:209], v[42:43], off offset:128
	global_load_dwordx4 v[210:213], v[42:43], off offset:192
	s_waitcnt vmcnt(4)
	v_pk_fma_f32 v[30:31], v[30:31], v[156:157], v[172:173]
	v_pk_fma_f32 v[32:33], v[32:33], v[158:159], v[174:175]
	v_pk_fma_f32 v[26:27], v[26:27], v[160:161], v[176:177]
	v_pk_fma_f32 v[28:29], v[28:29], v[162:163], v[178:179]
	v_pk_fma_f32 v[22:23], v[22:23], v[164:165], v[180:181]
	v_pk_fma_f32 v[24:25], v[24:25], v[166:167], v[182:183]
	v_pk_fma_f32 v[18:19], v[18:19], v[168:169], v[184:185]
	v_pk_fma_f32 v[20:21], v[20:21], v[170:171], v[186:187]
	global_store_dwordx4 v[44:45], v[30:33], off
	global_store_dwordx4 v[44:45], v[26:29], off offset:64
	global_store_dwordx4 v[44:45], v[22:25], off offset:128
	global_store_dwordx4 v[44:45], v[18:21], off offset:192
	v_add_co_u32_e32 v44, vcc, 0x10000, v44
	s_nop 1
	v_addc_co_u32_e32 v45, vcc, 0, v45, vcc
	s_waitcnt vmcnt(4)
	v_pk_fma_f32 v[14:15], v[14:15], v[156:157], v[198:199]
	v_pk_fma_f32 v[16:17], v[16:17], v[158:159], v[200:201]
	v_pk_fma_f32 v[10:11], v[10:11], v[160:161], v[202:203]
	v_pk_fma_f32 v[12:13], v[12:13], v[162:163], v[204:205]
	v_pk_fma_f32 v[6:7], v[6:7], v[164:165], v[206:207]
	v_pk_fma_f32 v[8:9], v[8:9], v[166:167], v[208:209]
	v_pk_fma_f32 v[2:3], v[2:3], v[168:169], v[210:211]
	v_pk_fma_f32 v[4:5], v[4:5], v[170:171], v[212:213]
	global_store_dwordx4 v[44:45], v[14:17], off
	global_store_dwordx4 v[44:45], v[10:13], off offset:64
	global_store_dwordx4 v[44:45], v[6:9], off offset:128
	global_store_dwordx4 v[44:45], v[2:5], off offset:192
	s_cbranch_scc0 .LBB0_54

; DI int tid_() { int t = threadIdx.x; asm volatile("" : "+v"(t)); return t; }
;     ...
;   const int tid = tid_(), w = tid >> 6, l = tid & 63, r16 = l & 15, q4 = l >> 4;
;   const int wm = w >> 2, wn = w & 3;
;   f32x4 acc[MT][4];
; #pragma unroll
;   for (int a = 0; a < MT; ++a)
; #pragma unroll
;     for (int b = 0; b < 4; ++b) { acc[a][b][0] = 0.f; acc[a][b][1] = 0.f; acc[a][b][2] = 0.f; acc[a][b][3] = 0.f; }
;   const int srow = tid >> 3, slog = (tid & 7) ^ ((tid >> 4) & 7);
;   const bf16_t* Ag = A + (size_t)(m0 + srow) * lda + slog * 8;
;   const bf16_t* Bg0 = B + (size_t)min(n0 + srow, N - 1) * ldb + slog * 8;
;   const bf16_t* Bg1 = B + (size_t)min(n0 + srow + 64, N - 1) * ldb + slog * 8;
;   const bf16_t* Bg2 = B + (size_t)min(n0 + srow + 128, N - 1) * ldb + slog * 8;
;   const bf16_t* Bg3 = B + (size_t)min(n0 + srow + 192, N - 1) * ldb + slog * 8;
;   char* wbase = smem + w * 1024;
;     ...
;   const int nk = K >> 6;
;   __syncthreads();
;   STAGE_TILE(0, 0)
;   asm volatile("s_waitcnt vmcnt(0)" ::: "memory");
;   __syncthreads();
; template <int TMI, class F>
; DI void for_tiles_xcd(int MT, int NT, const F& f) {
;     ...
;   for (int q = b; q < npieces; q += G) {
;     int mt, nt; decode(total_full + q / PIECES, mt, nt);
;     f(mt * 256 + (q % PIECES) * 64 * TMI, nt, std::integral_constant<int, TMI>{});
.LBB0_114:
	s_lshl_b32 s14, s22, 2
	s_sub_i32 s14, s30, s14
	s_lshl_b32 s23, s35, 8
	s_lshl_b32 s14, s14, 6
	v_mov_b32_e32 v18, v0
	s_add_i32 s23, s23, s14
	s_lshl_b32 s22, s34, 8
	s_mov_b64 s[14:15], 0x20000
	v_ashrrev_i32_e32 v6, 3, v18
	v_add_u32_e32 v2, s23, v6
	v_add_u32_e32 v6, s22, v6
	v_lshrrev_b32_e32 v19, 4, v18
	v_min_i32_e32 v12, 0x3bf, v6
	v_xor_b32_e32 v8, v19, v18
	v_ashrrev_i32_e32 v13, 31, v12
	v_min_i32_e32 v14, 0x37f, v6
	v_lshlrev_b32_e32 v8, 4, v8
	v_lshlrev_b64 v[12:13], 11, v[12:13]
	v_ashrrev_i32_e32 v15, 31, v14
	v_min_i32_e32 v16, 0x33f, v6
	v_and_b32_e32 v190, 0x70, v8
	v_lshl_add_u64 v[12:13], s[2:3], 0, v[12:13]
	v_lshlrev_b64 v[14:15], 11, v[14:15]
	v_ashrrev_i32_e32 v17, 31, v16
	v_lshl_add_u64 v[12:13], v[12:13], 0, v[190:191]
	v_lshl_add_u64 v[14:15], s[2:3], 0, v[14:15]
	v_lshlrev_b64 v[16:17], 11, v[16:17]
	v_ashrrev_i32_e32 v7, 6, v18
	v_ashrrev_i32_e32 v3, 31, v2
	v_readlane_b32 s52, v253, 40
	v_lshl_add_u64 v[12:13], v[12:13], 0, s[14:15]
	v_lshl_add_u64 v[14:15], v[14:15], 0, v[190:191]
	s_mov_b64 s[14:15], 0x40000
	v_lshl_add_u64 v[16:17], s[2:3], 0, v[16:17]
	v_lshlrev_b64 v[2:3], 11, v[2:3]
	v_readlane_b32 s53, v253, 41
	v_lshl_add_u64 v[14:15], v[14:15], 0, s[14:15]
	v_lshl_add_u64 v[16:17], v[16:17], 0, v[190:191]
	s_mov_b64 s[14:15], 0x60000
	v_lshl_add_u32 v48, v7, 10, 0
	v_lshl_add_u64 v[4:5], s[52:53], 0, v[2:3]
	v_min_i32_e32 v8, 0x3ff, v6
	v_lshl_add_u64 v[16:17], v[16:17], 0, s[14:15]
	v_readfirstlane_b32 s14, v48
	v_lshl_add_u64 v[4:5], v[4:5], 0, v[190:191]
	v_ashrrev_i32_e32 v9, 31, v8
	s_mov_b32 m0, s14
	v_lshlrev_b64 v[8:9], 11, v[8:9]
	s_barrier
	global_load_lds_dwordx4 v[4:5], off
	v_add_u32_e32 v4, 0x8000, v48
	v_lshl_add_u64 v[10:11], s[2:3], 0, v[8:9]
	v_readfirstlane_b32 s14, v4
	v_add_u32_e32 v4, 0xa000, v48
	v_lshl_add_u64 v[10:11], v[10:11], 0, v[190:191]
	s_mov_b32 m0, s14
	v_readfirstlane_b32 s14, v4
	v_add_u32_e32 v4, 0xc000, v48
	global_load_lds_dwordx4 v[10:11], off
	s_mov_b32 m0, s14
	v_readfirstlane_b32 s14, v4
	v_add_u32_e32 v4, 0xe000, v48
	global_load_lds_dwordx4 v[12:13], off
	s_mov_b32 m0, s14
	v_readfirstlane_b32 s14, v4
	global_load_lds_dwordx4 v[14:15], off
	s_mov_b32 m0, s14
	v_and_b32_e32 v46, 15, v18
	global_load_lds_dwordx4 v[16:17], off
	v_ashrrev_i32_e32 v44, 8, v18
	v_bfe_u32 v45, v18, 4, 2
	v_and_b32_e32 v47, 3, v7
	v_bfe_u32 v4, v18, 1, 3
	v_lshlrev_b32_e32 v5, 7, v46
	v_ashrrev_i32_e32 v7, 31, v6
	s_mov_b64 s[14:15], 0x33f
	v_lshl_or_b32 v52, v44, 12, v5
	v_lshl_or_b32 v51, v47, 13, v5
	v_bitop3_b32 v5, v19, v4, 3 bitop3:0x6c
	v_bitop3_b32 v4, v45, v4, 4 bitop3:0x36
	v_cmp_gt_i64_e32 vcc, s[14:15], v[6:7]
	v_lshlrev_b32_e32 v50, 4, v5
	v_lshlrev_b32_e32 v49, 4, v4
	v_cndmask_b32_e32 v5, 0, v7, vcc
	v_cndmask_b32_e32 v4, v227, v6, vcc
	v_bitop3_b32 v10, v19, 7, v18 bitop3:0x48
	v_lshlrev_b64 v[4:5], 11, v[4:5]
	v_lshlrev_b32_e32 v10, 4, v10
	s_mov_b64 s[14:15], 0x37f
	v_or_b32_e32 v4, v4, v10
	v_cmp_gt_i64_e32 vcc, s[14:15], v[6:7]
	v_lshl_add_u64 v[34:35], s[8:9], 0, v[4:5]
	s_mov_b64 s[14:15], 0x3bf
	v_cndmask_b32_e32 v5, 0, v7, vcc
	v_cndmask_b32_e32 v4, v197, v6, vcc
	v_lshlrev_b64 v[4:5], 11, v[4:5]
	v_or_b32_e32 v4, v4, v10
	v_cmp_gt_i64_e32 vcc, s[14:15], v[6:7]
	v_lshl_add_u64 v[36:37], s[10:11], 0, v[4:5]
	v_readlane_b32 s14, v253, 14
	v_cndmask_b32_e32 v5, 0, v7, vcc
	v_cndmask_b32_e32 v4, v195, v6, vcc
	s_waitcnt vmcnt(0)
	v_lshlrev_b64 v[4:5], 11, v[4:5]
	v_or_b32_e32 v2, v2, v10
	v_readlane_b32 s15, v253, 15
	v_or_b32_e32 v4, v4, v10
	v_or_b32_e32 v8, v8, v10
	v_lshl_add_u64 v[42:43], s[14:15], 0, v[2:3]
	v_mov_b32_e32 v2, 0
	s_mov_b32 s34, 0
	v_lshl_add_u64 v[38:39], s[12:13], 0, v[4:5]
	v_lshl_add_u64 v[40:41], s[4:5], 0, v[8:9]
	s_mov_b64 s[14:15], 0
	v_mov_b32_e32 v3, v2
	v_mov_b32_e32 v4, v2
	v_mov_b32_e32 v5, v2
	v_mov_b32_e32 v6, v2
	v_mov_b32_e32 v7, v2
	v_mov_b32_e32 v8, v2
	v_mov_b32_e32 v9, v2
	v_mov_b32_e32 v10, v2
	v_mov_b32_e32 v11, v2
	v_mov_b32_e32 v12, v2
	v_mov_b32_e32 v13, v2
	v_mov_b32_e32 v14, v2
	v_mov_b32_e32 v15, v2
	v_mov_b32_e32 v16, v2
	v_mov_b32_e32 v17, v2
	v_mov_b32_e32 v18, v2
	v_mov_b32_e32 v19, v2
	v_mov_b32_e32 v20, v2
	v_mov_b32_e32 v21, v2
	v_mov_b32_e32 v22, v2
	v_mov_b32_e32 v23, v2
	v_mov_b32_e32 v24, v2
	v_mov_b32_e32 v25, v2
	v_mov_b32_e32 v26, v2
	v_mov_b32_e32 v27, v2
	v_mov_b32_e32 v28, v2
	v_mov_b32_e32 v29, v2
	v_mov_b32_e32 v30, v2
	v_mov_b32_e32 v31, v2
	v_mov_b32_e32 v32, v2
	v_mov_b32_e32 v33, v2
	v_readlane_b32 s54, v253, 42
	v_readlane_b32 s55, v253, 43
	v_readlane_b32 s56, v253, 44
	v_readlane_b32 s57, v253, 45
	v_readlane_b32 s58, v253, 46
	v_readlane_b32 s59, v253, 47
	v_readlane_b32 s60, v253, 48
	v_readlane_b32 s61, v253, 49
	v_readlane_b32 s62, v253, 50
	v_readlane_b32 s63, v253, 51
	v_readlane_b32 s64, v253, 52
	v_readlane_b32 s65, v253, 53
	v_readlane_b32 s66, v253, 54
	v_readlane_b32 s67, v253, 55
	s_waitcnt vmcnt(0) lgkmcnt(0)
	s_barrier
	v_readfirstlane_b32 s100, v40
	v_readfirstlane_b32 s101, v41
	s_nop 0
	s_sub_u32 s100, s100, 0x80
	s_subb_u32 s101, s101, 0
	v_subrev_u32_e32 v176, s100, v42
	v_subrev_u32_e32 v177, s100, v40
	v_subrev_u32_e32 v178, s100, v38
	v_subrev_u32_e32 v179, s100, v36
	v_subrev_u32_e32 v180, s100, v34
; #define MFMA16(a, b, c) __builtin_amdgcn_mfma_f32_16x16x32_bf16((a), (b), (c), 0, 0, 0)
;     ...
;   for (int kt = 0; kt < nk; ++kt) {
;     const int buf = kt & 1;
;     const char* cA = smem + buf * STAGE + (wm * 32 * MI + r16) * 128;
;     const char* cB = smem + buf * STAGE + 32768 + (wn * 64 + r16) * 128;
; #pragma unroll
;     for (int k2 = 0; k2 < 2; ++k2) {
;       if (k2 == 1 && kt + 1 < nk) STAGE_TILE(buf ^ 1, (kt + 1) * 64)
;       const int po = ((4 * k2 + q4) ^ swz) * 16;
;       bf16x8 bf[4];
; #pragma unroll
;       for (int nt = 0; nt < 4; ++nt) bf[nt] = *(const bf16x8*)(cB + nt * 16 * 128 + po);
;       bf16x8 afc = *(const bf16x8*)(cA + po);
; #pragma unroll
;       for (int a = 0; a < MT; ++a) {
;         bf16x8 afn = afc;
;         if (a + 1 < MT) afn = *(const bf16x8*)(cA + (a + 1) * 16 * 128 + po);
;         __builtin_amdgcn_sched_barrier(0);
; #pragma unroll
;         for (int nt = 0; nt < 4; ++nt) acc[a][nt] = MFMA16(bf[nt], afc, acc[a][nt]);
;         __builtin_amdgcn_sched_barrier(0);
;         afc = afn;
;       }
;     }
;     asm volatile("s_waitcnt vmcnt(0)" ::: "memory");
;     __syncthreads();
;   }
.LBB0_115:
	s_and_b32 s35, s34, 0x10000
	s_add_i32 s36, s35, 0
	v_add_u32_e32 v78, s36, v51
	v_add_u32_e32 v66, v78, v50
	v_add_u32_e32 v53, s36, v52
	ds_read_b128 v[54:57], v66 offset:32768
	ds_read_b128 v[58:61], v66 offset:34816
	ds_read_b128 v[62:65], v66 offset:36864
	ds_read_b128 v[66:69], v66 offset:38912
	v_add_u32_e32 v74, v53, v50
	ds_read_b128 v[70:73], v74
	ds_read_b128 v[74:77], v74 offset:2048
	s_waitcnt lgkmcnt(1)
	v_mfma_f32_16x16x32_bf16 v[30:33], v[54:57], v[70:73], v[30:33]
	v_mfma_f32_16x16x32_bf16 v[26:29], v[58:61], v[70:73], v[26:29]
	v_mfma_f32_16x16x32_bf16 v[22:25], v[62:65], v[70:73], v[22:25]
	v_mfma_f32_16x16x32_bf16 v[18:21], v[66:69], v[70:73], v[18:21]
	s_waitcnt lgkmcnt(0)
	v_mfma_f32_16x16x32_bf16 v[14:17], v[54:57], v[74:77], v[14:17]
	v_mfma_f32_16x16x32_bf16 v[10:13], v[58:61], v[74:77], v[10:13]
	v_mfma_f32_16x16x32_bf16 v[6:9], v[62:65], v[74:77], v[6:9]
	v_mfma_f32_16x16x32_bf16 v[2:5], v[66:69], v[74:77], v[2:5]
	s_xor_b32 s35, s35, 0x10000
	v_readfirstlane_b32 s36, v48
	s_nop 0
	s_add_u32 s36, s36, s35
	s_add_u32 m0, s36, 0x0
	s_nop 0
	global_load_lds_dwordx4 v176, s[100:101]
	s_add_u32 m0, s36, 0x8000
	s_nop 0
	global_load_lds_dwordx4 v177, s[100:101]
	s_add_u32 m0, s36, 0xa000
	s_nop 0
	global_load_lds_dwordx4 v178, s[100:101]
	s_add_u32 m0, s36, 0xc000
	s_nop 0
	global_load_lds_dwordx4 v179, s[100:101]
	s_add_u32 m0, s36, 0xe000
	s_nop 0
	global_load_lds_dwordx4 v180, s[100:101]
	v_add_u32_e32 v66, v78, v49
	ds_read_b128 v[54:57], v66 offset:32768
	ds_read_b128 v[58:61], v66 offset:34816
	ds_read_b128 v[62:65], v66 offset:36864
	ds_read_b128 v[66:69], v66 offset:38912
	v_add_u32_e32 v53, v53, v49
	ds_read_b128 v[70:73], v53
	ds_read_b128 v[74:77], v53 offset:2048
	s_waitcnt lgkmcnt(0)
	v_mfma_f32_16x16x32_bf16 v[30:33], v[54:57], v[70:73], v[30:33]
	v_mfma_f32_16x16x32_bf16 v[26:29], v[58:61], v[70:73], v[26:29]
	v_mfma_f32_16x16x32_bf16 v[22:25], v[62:65], v[70:73], v[22:25]
	v_mfma_f32_16x16x32_bf16 v[18:21], v[66:69], v[70:73], v[18:21]
	v_mfma_f32_16x16x32_bf16 v[14:17], v[54:57], v[74:77], v[14:17]
	v_mfma_f32_16x16x32_bf16 v[10:13], v[58:61], v[74:77], v[10:13]
	v_mfma_f32_16x16x32_bf16 v[6:9], v[62:65], v[74:77], v[6:9]
	v_mfma_f32_16x16x32_bf16 v[2:5], v[66:69], v[74:77], v[2:5]
	s_waitcnt vmcnt(0)
	s_add_u32 s100, s100, 0x80
	s_addc_u32 s101, s101, 0
	s_add_u32 s14, s14, 0x80
	s_addc_u32 s15, s15, 0
	s_add_i32 s34, s34, 0x10000
	s_cmpk_eq_i32 s14, 0x780
	s_waitcnt vmcnt(0)
	s_barrier
	s_cbranch_scc0 .LBB0_115
	s_add_i32 s14, 0, 0x10000
	v_add_u32_e32 v42, s14, v52
	v_readlane_b32 s14, v254, 18
	s_nop 1
	v_add_u32_e32 v43, s14, v51
	v_add_u32_e32 v48, v43, v50
	ds_read_b128 v[34:37], v48
	ds_read_b128 v[38:41], v48 offset:2048
	ds_read_b128 v[52:55], v48 offset:4096
	ds_read_b128 v[56:59], v48 offset:6144
	v_add_u32_e32 v48, v42, v50
	ds_read_b128 v[60:63], v48
	ds_read_b128 v[64:67], v48 offset:2048
	s_waitcnt lgkmcnt(1)
	v_mfma_f32_16x16x32_bf16 v[30:33], v[34:37], v[60:63], v[30:33]
	v_mfma_f32_16x16x32_bf16 v[26:29], v[38:41], v[60:63], v[26:29]
	v_mfma_f32_16x16x32_bf16 v[22:25], v[52:55], v[60:63], v[22:25]
	v_mfma_f32_16x16x32_bf16 v[18:21], v[56:59], v[60:63], v[18:21]
	s_waitcnt lgkmcnt(0)
	v_mfma_f32_16x16x32_bf16 v[14:17], v[34:37], v[64:67], v[14:17]
	v_mfma_f32_16x16x32_bf16 v[10:13], v[38:41], v[64:67], v[10:13]
	v_mfma_f32_16x16x32_bf16 v[6:9], v[52:55], v[64:67], v[6:9]
	v_mfma_f32_16x16x32_bf16 v[2:5], v[56:59], v[64:67], v[2:5]
	v_add_u32_e32 v43, v43, v49
	ds_read_b128 v[34:37], v43
	ds_read_b128 v[38:41], v43 offset:2048
	ds_read_b128 v[50:53], v43 offset:4096
	ds_read_b128 v[54:57], v43 offset:6144
	v_add_u32_e32 v42, v42, v49
	ds_read_b128 v[58:61], v42
	ds_read_b128 v[62:65], v42 offset:2048
	s_waitcnt lgkmcnt(1)
	v_mfma_f32_16x16x32_bf16 v[30:33], v[34:37], v[58:61], v[30:33]
	v_mfma_f32_16x16x32_bf16 v[26:29], v[38:41], v[58:61], v[26:29]
	v_mfma_f32_16x16x32_bf16 v[22:25], v[50:53], v[58:61], v[22:25]
	v_mfma_f32_16x16x32_bf16 v[18:21], v[54:57], v[58:61], v[18:21]
	s_waitcnt lgkmcnt(0)
	v_mfma_f32_16x16x32_bf16 v[14:17], v[34:37], v[62:65], v[14:17]
	v_mfma_f32_16x16x32_bf16 v[10:13], v[38:41], v[62:65], v[10:13]
	v_mfma_f32_16x16x32_bf16 v[6:9], v[50:53], v[62:65], v[6:9]
	v_mfma_f32_16x16x32_bf16 v[2:5], v[54:57], v[62:65], v[2:5]
	v_or_b32_e32 v35, s23, v46
	v_lshlrev_b32_e32 v34, 6, v47
	v_lshl_add_u32 v54, v44, 5, v35
	v_lshlrev_b32_e32 v35, 2, v45
	v_or3_b32 v38, v34, v35, s22
	v_mul_hi_i32 v34, v54, s1
	v_lshrrev_b32_e32 v35, 31, v34
	v_ashrrev_i32_e32 v34, 11, v34
	v_add_u32_e32 v34, v34, v35
	v_mad_i32_i24 v35, v34, s90, v54
	s_movk_i32 s34, 0x100
	v_cmp_gt_i32_e32 vcc, s34, v35
	v_mov_b32_e32 v55, s20
	v_mov_b32_e32 v56, s21
	v_readlane_b32 s22, v252, 1
	v_cndmask_b32_e32 v190, v55, v56, vcc
	v_readlane_b32 s23, v252, 2
	s_waitcnt vmcnt(0)
	s_barrier
; DI void phase_resid(char* smem, const Params& p, int layer, const bf16_t* A, int K, const bf16_t* W, int gate_idx, bool first) {
;     ...
;   auto ep = [&](int row, int col, float v0, float v1, float v2, float v3) {
;     const int b = row / TT, t = row - b * TT;
;     const float4 g = *(const float4*)(p.mod + (size_t)(layer * 5 + (t < CTXL ? 4 : b)) * 6144 + gate_idx * 1024 + col);
;     const float4 xo = *(const float4*)(xsrc_row(p, first, row) + col);
;     *(float4*)(xdst_row(p, row) + col) = make_float4(xo.x + g.x * v0, xo.y + g.y * v1, xo.z + g.z * v2, xo.w + g.w * v3);
;   };
	s_nop 0
	v_lshl_add_u64 v[42:43], s[22:23], 0, v[190:191]
	global_load_dwordx2 v[42:43], v[42:43], off
	v_add_u32_e32 v36, 0xffffff00, v35
	v_ashrrev_i32_e32 v37, 31, v35
	v_readlane_b32 s36, v254, 1
	v_cndmask_b32_e64 v39, v34, 4, vcc
	v_cndmask_b32_e32 v37, 0, v37, vcc
	v_cndmask_b32_e32 v36, v36, v35, vcc
	v_ashrrev_i32_e32 v35, 31, v34
	v_cndmask_b32_e64 v40, 25, 20, vcc
	v_readlane_b32 s37, v254, 2
	v_readlane_b32 s68, v252, 5
	v_lshlrev_b64 v[44:45], v40, v[34:35]
	v_lshlrev_b64 v[46:47], 12, v[36:37]
	v_add_u32_e32 v34, s17, v39
	v_mov_b64_e32 v[36:37], s[36:37]
	s_movk_i32 s35, 0x6000
	v_readlane_b32 s80, v252, 17
	v_readlane_b32 s81, v252, 18
	v_readlane_b32 s82, v252, 19
	v_readlane_b32 s83, v252, 20
	v_mad_i64_i32 v[34:35], s[14:15], v34, s35, v[36:37]
	s_mov_b64 s[36:37], 0x2000
	v_ashrrev_i32_e32 v39, 31, v38
	v_mov_b32_e32 v57, s81
	v_mov_b32_e32 v58, s83
	v_mov_b32_e32 v59, s80
	v_mov_b32_e32 v60, s82
	v_lshl_add_u64 v[40:41], v[34:35], 0, s[36:37]
	v_lshlrev_b64 v[34:35], 2, v[38:39]
	v_cndmask_b32_e32 v51, v57, v58, vcc
	v_cndmask_b32_e32 v50, v59, v60, vcc
	v_lshl_add_u64 v[48:49], v[40:41], 0, v[34:35]
	v_readlane_b32 s38, v254, 3
	v_readlane_b32 s39, v254, 4
	v_readlane_b32 s40, v254, 5
	v_readlane_b32 s41, v254, 6
	v_readlane_b32 s42, v254, 7
	v_readlane_b32 s43, v254, 8
	v_readlane_b32 s44, v254, 9
	v_readlane_b32 s45, v254, 10
	v_readlane_b32 s46, v254, 11
	v_readlane_b32 s47, v254, 12
	v_readlane_b32 s48, v254, 13
	v_readlane_b32 s49, v254, 14
	v_readlane_b32 s50, v254, 15
	v_readlane_b32 s51, v254, 16
	s_add_i32 s30, s30, s27
	s_cmp_ge_i32 s30, s16
	v_readlane_b32 s69, v252, 6
	v_readlane_b32 s70, v252, 7
	v_readlane_b32 s71, v252, 8
	v_readlane_b32 s72, v252, 9
	v_readlane_b32 s73, v252, 10
	v_readlane_b32 s74, v252, 11
	v_readlane_b32 s75, v252, 12
	v_readlane_b32 s76, v252, 13
	v_readlane_b32 s77, v252, 14
	v_readlane_b32 s78, v252, 15
	v_readlane_b32 s79, v252, 16
	s_waitcnt vmcnt(0)
	v_lshl_add_u64 v[42:43], v[42:43], 0, v[44:45]
	v_lshl_add_u64 v[42:43], v[42:43], 0, v[46:47]
	v_lshl_add_u64 v[44:45], v[50:51], 0, v[44:45]
	v_lshl_add_u64 v[42:43], v[42:43], 0, v[34:35]
	v_lshl_add_u64 v[44:45], v[44:45], 0, v[46:47]
	v_lshl_add_u64 v[44:45], v[44:45], 0, v[34:35]
	v_readlane_b32 s36, v255, 12
	v_readlane_b32 s37, v255, 13
	v_readlane_b32 s38, v255, 14
	v_readlane_b32 s39, v255, 15
	v_readlane_b32 s40, v255, 16
	v_readlane_b32 s41, v255, 17
	v_readlane_b32 s42, v255, 18
	v_readlane_b32 s43, v255, 19
	v_readlane_b32 s44, v255, 20
	v_readlane_b32 s45, v255, 21
	v_readlane_b32 s46, v255, 22
	v_readlane_b32 s47, v255, 23
	v_readlane_b32 s48, v255, 24
	v_readlane_b32 s49, v255, 25
	v_readlane_b32 s50, v255, 26
	v_readlane_b32 s51, v255, 27
	global_load_dwordx4 v[156:159], v[48:49], off
	global_load_dwordx4 v[160:163], v[48:49], off offset:64
	global_load_dwordx4 v[164:167], v[48:49], off offset:128
	global_load_dwordx4 v[168:171], v[48:49], off offset:192
	global_load_dwordx4 v[172:175], v[42:43], off
	global_load_dwordx4 v[176:179], v[42:43], off offset:64
	global_load_dwordx4 v[180:183], v[42:43], off offset:128
	global_load_dwordx4 v[184:187], v[42:43], off offset:192
	v_add_co_u32_e32 v42, vcc, 0x10000, v42
	s_nop 1
	v_addc_co_u32_e32 v43, vcc, 0, v43, vcc
	global_load_dwordx4 v[198:201], v[42:43], off
	global_load_dwordx4 v[202:205], v[42:43], off offset:64
	global_load_dwordx4 v[206:209], v[42:43], off offset:128
	global_load_dwordx4 v[210:213], v[42:43], off offset:192
	s_waitcnt vmcnt(4)
	v_pk_fma_f32 v[30:31], v[30:31], v[156:157], v[172:173]
	v_pk_fma_f32 v[32:33], v[32:33], v[158:159], v[174:175]
	v_pk_fma_f32 v[26:27], v[26:27], v[160:161], v[176:177]
	v_pk_fma_f32 v[28:29], v[28:29], v[162:163], v[178:179]
	v_pk_fma_f32 v[22:23], v[22:23], v[164:165], v[180:181]
	v_pk_fma_f32 v[24:25], v[24:25], v[166:167], v[182:183]
	v_pk_fma_f32 v[18:19], v[18:19], v[168:169], v[184:185]
	v_pk_fma_f32 v[20:21], v[20:21], v[170:171], v[186:187]
	global_store_dwordx4 v[44:45], v[30:33], off
	global_store_dwordx4 v[44:45], v[26:29], off offset:64
	global_store_dwordx4 v[44:45], v[22:25], off offset:128
	global_store_dwordx4 v[44:45], v[18:21], off offset:192
	v_add_co_u32_e32 v44, vcc, 0x10000, v44
	s_nop 1
	v_addc_co_u32_e32 v45, vcc, 0, v45, vcc
	s_waitcnt vmcnt(4)
	v_pk_fma_f32 v[14:15], v[14:15], v[156:157], v[198:199]
	v_pk_fma_f32 v[16:17], v[16:17], v[158:159], v[200:201]
	v_pk_fma_f32 v[10:11], v[10:11], v[160:161], v[202:203]
	v_pk_fma_f32 v[12:13], v[12:13], v[162:163], v[204:205]
	v_pk_fma_f32 v[6:7], v[6:7], v[164:165], v[206:207]
	v_pk_fma_f32 v[8:9], v[8:9], v[166:167], v[208:209]
	v_pk_fma_f32 v[2:3], v[2:3], v[168:169], v[210:211]
	v_pk_fma_f32 v[4:5], v[4:5], v[170:171], v[212:213]
	global_store_dwordx4 v[44:45], v[14:17], off
	global_store_dwordx4 v[44:45], v[10:13], off offset:64
	global_store_dwordx4 v[44:45], v[6:9], off offset:128
	global_store_dwordx4 v[44:45], v[2:5], off offset:192
	s_cbranch_scc0 .LBB0_110
